# W_up GEMM K-loop: LDS-DMA staging rebalanced from 2+6 to 4+4 pieces per super-phase with re-derived vmcnt 8/4/8/4 (on top of previous edits)
# baseline (speedup 1.0000x reference)
;     __host__ __device__ bool next(int i, Unit& u) const { const int L = i * G + c; if (L >= nunits) return false; u.pm = pm; u.pn = L & 7; u.ko = (L >> 3) * klen; return true; }
; #define PG8_STAGE(bufoff, gbase, voff) do { _Pragma("unroll") for (int _i = 0; _i < 2; ++_i) \
;         __builtin_amdgcn_global_load_lds((const unsigned*)((const char*)(gbase) + (voff)[_i]), (PG8_LAS unsigned*)(lds + (bufoff) + ldsw + _i * 8192), 16, 0, 0); } while (0)
; #define PG8_LDA(dst, b, h) do { _Pragma("unroll") for (int m = 0; m < 4; ++m) _Pragma("unroll") for (int k = 0; k < 2; ++k) dst[m][k] = *(const PG8_LAS bf16x8*)(lds + PG8_SA(b, h) + aoff + m * 2048 + k * 1024); } while (0)
; #define PG8_LDB(dst, b, h) do { _Pragma("unroll") for (int n = 0; n < 2; ++n) _Pragma("unroll") for (int k = 0; k < 2; ++k) dst[n][k] = *(const PG8_LAS bf16x8*)(lds + PG8_SB(b, h) + boff + n * 2048 + k * 1024); } while (0)
; #define PG8_WAIT_V(n) asm volatile("s_waitcnt vmcnt(" #n ")" ::: "memory")
; #define PG8_WAIT_L(n) asm volatile("s_waitcnt lgkmcnt(" #n ")" ::: "memory")
; #define PG8_BAR __builtin_amdgcn_s_barrier()
; template <class Epi, class Sched, bool ALIGN_EPI = false, bool SP2 = false>
; __device__ __forceinline__ void gemm_phase(PG8_LAS unsigned char* lds, const Gemm g, const Sched& S, const Epi& E) {
;     ...
;         const bool has_next = S.next(ui + 1, nxt);
;         const char* nA = has_next ? (const char*)g.A + (size_t)nxt.pm * tstep + (size_t)nxt.ko * 2 : cA; const char* nB = has_next ? (const char*)g.Bt + (size_t)nxt.pn * tstep + (size_t)nxt.ko * 2 : cB;
;         for (int t = 0; t < nt; t += 2) {
;             const bool last = (t == nt - 2);
;             const char* a1 = cA + (size_t)(t + 1) * kstep;
;             const char* a2 = last ? nA : cA + (size_t)(t + 2) * kstep; const char* b2 = last ? nB : cB + (size_t)(t + 2) * kstep;
;             const char* a3 = a2 + kstep; const char* b3 = b2 + kstep;
;             if (last && has_next) S.a_ready(nxt);
;             if constexpr (SP2) {
;             PG8_LDB(B0, 0, 0); PG8_LDB(B1, 0, 1); PG8_SCHED; PG8_LDA(At, 0, 0); PG8_STAGE(PG8_SA(1, 1), a1 + hstep, voffA);
;             PG8_WAIT_V(8); PG8_WAIT_L(0); PG8_BAR; PG8_MMA(0, 0, At, B0); PG8_MMA(0, 1, At, B1); PG8_BAR; PG8_SCHED;
;             PG8_LDA(At, 0, 1); PG8_STAGE(PG8_SB(0, 0), b2, voffB); PG8_STAGE(PG8_SB(0, 1), b2 + hstep, voffB); PG8_STAGE(PG8_SA(0, 0), a2, voffA);
.LBB0_1009:
	s_ashr_i32 s15, s14, 31
	s_lshl_b64 s[16:17], s[14:15], 20
	s_add_u32 s16, s48, s16
	s_addc_u32 s17, s49, s17
	s_and_b64 s[18:19], s[8:9], exec
	s_cselect_b32 s15, s17, s23
	s_cselect_b32 s30, s16, s22
	s_ashr_i32 s13, s12, 31
	s_lshl_b64 s[18:19], s[12:13], 20
	s_add_u32 s18, s54, s18
	s_addc_u32 s19, s55, s19
	s_and_b64 s[36:37], s[8:9], exec
	s_cselect_b32 s13, s19, s27
	s_cselect_b32 s31, s18, s26
	v_lshl_add_u64 v[226:227], s[22:23], 0, v[132:133]
	v_lshl_add_u64 v[228:229], s[22:23], 0, v[130:131]
	s_add_u32 s22, s22, 0x80080
	s_addc_u32 s23, s23, 0
	s_add_u32 s56, s26, 0x100
	v_mov_b32_e32 v0, 0
	s_addc_u32 s73, s27, 0
	s_mov_b32 s76, -2
	v_mov_b32_e32 v1, v0
	v_mov_b32_e32 v2, v0
	v_mov_b32_e32 v3, v0
	v_mov_b32_e32 v4, v0
	v_mov_b32_e32 v5, v0
	v_mov_b32_e32 v6, v0
	v_mov_b32_e32 v7, v0
	v_mov_b32_e32 v16, v0
	v_mov_b32_e32 v17, v0
	v_mov_b32_e32 v18, v0
	v_mov_b32_e32 v19, v0
	v_mov_b32_e32 v20, v0
	v_mov_b32_e32 v21, v0
	v_mov_b32_e32 v22, v0
	v_mov_b32_e32 v23, v0
	v_mov_b32_e32 v32, v0
	v_mov_b32_e32 v33, v0
	v_mov_b32_e32 v34, v0
	v_mov_b32_e32 v35, v0
	v_mov_b32_e32 v36, v0
	v_mov_b32_e32 v37, v0
	v_mov_b32_e32 v38, v0
	v_mov_b32_e32 v39, v0
	v_mov_b32_e32 v48, v0
	v_mov_b32_e32 v49, v0
	v_mov_b32_e32 v50, v0
	v_mov_b32_e32 v51, v0
	v_mov_b32_e32 v52, v0
	v_mov_b32_e32 v53, v0
	v_mov_b32_e32 v54, v0
	v_mov_b32_e32 v55, v0
	v_mov_b32_e32 v8, v0
	v_mov_b32_e32 v9, v0
	v_mov_b32_e32 v10, v0
	v_mov_b32_e32 v11, v0
	v_mov_b32_e32 v12, v0
	v_mov_b32_e32 v13, v0
	v_mov_b32_e32 v14, v0
	v_mov_b32_e32 v15, v0
	v_mov_b32_e32 v24, v0
	v_mov_b32_e32 v25, v0
	v_mov_b32_e32 v26, v0
	v_mov_b32_e32 v27, v0
	v_mov_b32_e32 v28, v0
	v_mov_b32_e32 v29, v0
	v_mov_b32_e32 v30, v0
	v_mov_b32_e32 v31, v0
	v_mov_b32_e32 v40, v0
	v_mov_b32_e32 v41, v0
	v_mov_b32_e32 v42, v0
	v_mov_b32_e32 v43, v0
	v_mov_b32_e32 v44, v0
	v_mov_b32_e32 v45, v0
	v_mov_b32_e32 v46, v0
	v_mov_b32_e32 v47, v0
	v_mov_b32_e32 v56, v0
	v_mov_b32_e32 v57, v0
	v_mov_b32_e32 v58, v0
	v_mov_b32_e32 v59, v0
	v_mov_b32_e32 v60, v0
	v_mov_b32_e32 v61, v0
	v_mov_b32_e32 v62, v0
	v_mov_b32_e32 v63, v0
	v_mov_b32_e32 v64, v0
	v_mov_b32_e32 v65, v0
	v_mov_b32_e32 v66, v0
	v_mov_b32_e32 v67, v0
	v_mov_b32_e32 v68, v0
	v_mov_b32_e32 v69, v0
	v_mov_b32_e32 v70, v0
	v_mov_b32_e32 v71, v0
	v_mov_b32_e32 v80, v0
	v_mov_b32_e32 v81, v0
	v_mov_b32_e32 v82, v0
	v_mov_b32_e32 v83, v0
	v_mov_b32_e32 v84, v0
	v_mov_b32_e32 v85, v0
	v_mov_b32_e32 v86, v0
	v_mov_b32_e32 v87, v0
	v_mov_b32_e32 v96, v0
	v_mov_b32_e32 v97, v0
	v_mov_b32_e32 v98, v0
	v_mov_b32_e32 v99, v0
	v_mov_b32_e32 v100, v0
	v_mov_b32_e32 v101, v0
	v_mov_b32_e32 v102, v0
	v_mov_b32_e32 v103, v0
	v_mov_b32_e32 v112, v0
	v_mov_b32_e32 v113, v0
	v_mov_b32_e32 v114, v0
	v_mov_b32_e32 v115, v0
	v_mov_b32_e32 v116, v0
	v_mov_b32_e32 v117, v0
	v_mov_b32_e32 v118, v0
	v_mov_b32_e32 v119, v0
	v_mov_b32_e32 v72, v0
	v_mov_b32_e32 v73, v0
	v_mov_b32_e32 v74, v0
	v_mov_b32_e32 v75, v0
	v_mov_b32_e32 v76, v0
	v_mov_b32_e32 v77, v0
	v_mov_b32_e32 v78, v0
	v_mov_b32_e32 v79, v0
	v_mov_b32_e32 v88, v0
	v_mov_b32_e32 v89, v0
	v_mov_b32_e32 v90, v0
	v_mov_b32_e32 v91, v0
	v_mov_b32_e32 v92, v0
	v_mov_b32_e32 v93, v0
	v_mov_b32_e32 v94, v0
	v_mov_b32_e32 v95, v0
	v_mov_b32_e32 v104, v0
	v_mov_b32_e32 v105, v0
	v_mov_b32_e32 v106, v0
	v_mov_b32_e32 v107, v0
	v_mov_b32_e32 v108, v0
	v_mov_b32_e32 v109, v0
	v_mov_b32_e32 v110, v0
	v_mov_b32_e32 v111, v0
	v_mov_b32_e32 v120, v0
	v_mov_b32_e32 v121, v0
	v_mov_b32_e32 v122, v0
	v_mov_b32_e32 v123, v0
	v_mov_b32_e32 v124, v0
	v_mov_b32_e32 v125, v0
	v_mov_b32_e32 v126, v0
	v_mov_b32_e32 v127, v0
.LBB0_1010:
	s_add_u32 s26, s22, 0xfff80080
	s_addc_u32 s27, s23, -1
	s_add_i32 s43, 0, 0x10000
	s_cmp_eq_u32 s76, 28
	s_cselect_b32 s37, s15, s27
	s_cselect_b32 s36, s30, s26
	v_add_u32_e32 v138, s43, v151
	s_cselect_b32 s27, s13, s73
	s_cselect_b32 s26, s31, s56
	s_add_i32 s61, 0, 0x14000
	ds_read_b128 v[146:149], v138
	ds_read_b128 v[156:159], v138 offset:1024
	ds_read_b128 v[160:163], v138 offset:2048
	ds_read_b128 v[164:167], v138 offset:3072
	v_add_u32_e32 v138, s61, v151
	ds_read_b128 v[168:171], v138
	ds_read_b128 v[172:175], v138 offset:1024
	ds_read_b128 v[176:179], v138 offset:2048
	ds_read_b128 v[180:183], v138 offset:3072
	v_lshl_add_u64 v[138:139], s[22:23], 0, v[134:135]
	s_add_i32 m0, s63, 0xc000
	ds_read_b128 v[184:187], v154
	ds_read_b128 v[188:191], v154 offset:1024
	ds_read_b128 v[192:195], v154 offset:2048
	ds_read_b128 v[196:199], v154 offset:3072
	ds_read_b128 v[208:211], v154 offset:4096
	ds_read_b128 v[212:215], v154 offset:5120
	ds_read_b128 v[216:219], v154 offset:6144
	ds_read_b128 v[220:223], v154 offset:7168
	global_load_lds_dwordx4 v[138:139], off
	v_lshl_add_u64 v[138:139], s[22:23], 0, v[136:137]
	s_add_i32 m0, s63, 0xe000
	s_nop 0
	global_load_lds_dwordx4 v[138:139], off
	v_lshl_add_u64 v[138:139], v[226:227], 0, s[84:85]
	s_mov_b32 m0, s70
	s_nop 0
	global_load_lds_dwordx4 v[138:139], off
	v_lshl_add_u64 v[138:139], v[228:229], 0, s[84:85]
	s_mov_b32 m0, s71
	s_nop 0
	global_load_lds_dwordx4 v[138:139], off
	s_waitcnt vmcnt(8)
	s_waitcnt lgkmcnt(0)
	s_barrier
; #define PG8_STAGE(bufoff, gbase, voff) do { _Pragma("unroll") for (int _i = 0; _i < 2; ++_i) \
;         __builtin_amdgcn_global_load_lds((const unsigned*)((const char*)(gbase) + (voff)[_i]), (PG8_LAS unsigned*)(lds + (bufoff) + ldsw + _i * 8192), 16, 0, 0); } while (0)
; #define PG8_LDA(dst, b, h) do { _Pragma("unroll") for (int m = 0; m < 4; ++m) _Pragma("unroll") for (int k = 0; k < 2; ++k) dst[m][k] = *(const PG8_LAS bf16x8*)(lds + PG8_SA(b, h) + aoff + m * 2048 + k * 1024); } while (0)
; #define PG8_MMA(ai, bj, At, Bt) do { __builtin_amdgcn_s_setprio(1); _Pragma("unroll") for (int m = 0; m < 4; ++m) _Pragma("unroll") for (int n = 0; n < 2; ++n) _Pragma("unroll") for (int k = 0; k < 2; ++k) \
;         acc[ai][bj][m][n] = __builtin_amdgcn_mfma_f32_16x16x32_bf16(Bt[n][k], At[m][k], acc[ai][bj][m][n], 0, 0, 0); __builtin_amdgcn_s_setprio(0); } while (0)
; #define PG8_WAIT_V(n) asm volatile("s_waitcnt vmcnt(" #n ")" ::: "memory")
; #define PG8_WAIT_L(n) asm volatile("s_waitcnt lgkmcnt(" #n ")" ::: "memory")
; #define PG8_BAR __builtin_amdgcn_s_barrier()
; #define PG8_SCHED __builtin_amdgcn_sched_barrier(0)
; template <class Epi, class Sched, bool ALIGN_EPI = false, bool SP2 = false>
; __device__ __forceinline__ void gemm_phase(PG8_LAS unsigned char* lds, const Gemm g, const Sched& S, const Epi& E) {
;     ...
;             PG8_WAIT_V(8); PG8_WAIT_L(0); PG8_BAR; PG8_MMA(0, 0, At, B0); PG8_MMA(0, 1, At, B1); PG8_BAR; PG8_SCHED;
;             PG8_LDA(At, 0, 1); PG8_STAGE(PG8_SB(0, 0), b2, voffB); PG8_STAGE(PG8_SB(0, 1), b2 + hstep, voffB); PG8_STAGE(PG8_SA(0, 0), a2, voffA);
;             PG8_WAIT_V(8); PG8_WAIT_L(0); PG8_BAR; PG8_MMA(1, 0, At, B0); PG8_MMA(1, 1, At, B1); PG8_BAR; PG8_SCHED;
	s_setprio 1
	s_waitcnt lgkmcnt(0)
	v_mfma_f32_16x16x32_bf16 v[124:127], v[146:149], v[184:187], v[124:127]
	v_mfma_f32_16x16x32_bf16 v[120:123], v[160:163], v[184:187], v[120:123]
	v_mfma_f32_16x16x32_bf16 v[108:111], v[146:149], v[192:195], v[108:111]
	v_mfma_f32_16x16x32_bf16 v[104:107], v[160:163], v[192:195], v[104:107]
	v_mfma_f32_16x16x32_bf16 v[92:95], v[146:149], v[208:211], v[92:95]
	v_mfma_f32_16x16x32_bf16 v[88:91], v[160:163], v[208:211], v[88:91]
	v_mfma_f32_16x16x32_bf16 v[76:79], v[146:149], v[216:219], v[76:79]
	v_mfma_f32_16x16x32_bf16 v[72:75], v[160:163], v[216:219], v[72:75]
	v_mfma_f32_16x16x32_bf16 v[124:127], v[156:159], v[188:191], v[124:127]
	v_mfma_f32_16x16x32_bf16 v[120:123], v[164:167], v[188:191], v[120:123]
	v_mfma_f32_16x16x32_bf16 v[108:111], v[156:159], v[196:199], v[108:111]
	v_mfma_f32_16x16x32_bf16 v[104:107], v[164:167], v[196:199], v[104:107]
	v_mfma_f32_16x16x32_bf16 v[92:95], v[156:159], v[212:215], v[92:95]
	v_mfma_f32_16x16x32_bf16 v[88:91], v[164:167], v[212:215], v[88:91]
	v_mfma_f32_16x16x32_bf16 v[76:79], v[156:159], v[220:223], v[76:79]
	v_mfma_f32_16x16x32_bf16 v[72:75], v[164:167], v[220:223], v[72:75]
	s_setprio 0
	s_setprio 1
	v_mfma_f32_16x16x32_bf16 v[116:119], v[168:171], v[184:187], v[116:119]
	v_mfma_f32_16x16x32_bf16 v[112:115], v[176:179], v[184:187], v[112:115]
	v_mfma_f32_16x16x32_bf16 v[100:103], v[168:171], v[192:195], v[100:103]
	v_mfma_f32_16x16x32_bf16 v[96:99], v[176:179], v[192:195], v[96:99]
	v_mfma_f32_16x16x32_bf16 v[84:87], v[168:171], v[208:211], v[84:87]
	v_mfma_f32_16x16x32_bf16 v[80:83], v[176:179], v[208:211], v[80:83]
	v_mfma_f32_16x16x32_bf16 v[68:71], v[168:171], v[216:219], v[68:71]
	v_mfma_f32_16x16x32_bf16 v[64:67], v[176:179], v[216:219], v[64:67]
	v_mfma_f32_16x16x32_bf16 v[116:119], v[172:175], v[188:191], v[116:119]
	v_mfma_f32_16x16x32_bf16 v[112:115], v[180:183], v[188:191], v[112:115]
	v_mfma_f32_16x16x32_bf16 v[100:103], v[172:175], v[196:199], v[100:103]
	v_mfma_f32_16x16x32_bf16 v[96:99], v[180:183], v[196:199], v[96:99]
	v_mfma_f32_16x16x32_bf16 v[84:87], v[172:175], v[212:215], v[84:87]
	v_mfma_f32_16x16x32_bf16 v[80:83], v[180:183], v[212:215], v[80:83]
	v_mfma_f32_16x16x32_bf16 v[68:71], v[172:175], v[220:223], v[68:71]
	v_mfma_f32_16x16x32_bf16 v[64:67], v[180:183], v[220:223], v[64:67]
	s_setprio 0
	s_barrier
	s_add_i32 s43, s43, s62
	v_lshl_add_u64 v[138:139], s[26:27], 0, v[140:141]
	s_mov_b32 m0, s43
	ds_read_b128 v[184:187], v154 offset:16384
	ds_read_b128 v[188:191], v154 offset:17408
	ds_read_b128 v[192:195], v154 offset:18432
	ds_read_b128 v[196:199], v154 offset:19456
	ds_read_b128 v[208:211], v154 offset:20480
	ds_read_b128 v[212:215], v154 offset:21504
	ds_read_b128 v[216:219], v154 offset:22528
	ds_read_b128 v[220:223], v154 offset:23552
	global_load_lds_dwordx4 v[138:139], off
	s_add_i32 m0, s43, 0x2000
	s_add_u32 s80, s26, 0x80000
	v_lshl_add_u64 v[224:225], s[26:27], 0, v[128:129]
	s_addc_u32 s81, s27, 0
	s_add_i32 s43, s61, s62
	global_load_lds_dwordx4 v[224:225], off
	v_lshl_add_u64 v[226:227], s[80:81], 0, v[140:141]
	s_mov_b32 m0, s43
	global_load_lds_dwordx4 v[226:227], off
	v_lshl_add_u64 v[226:227], s[80:81], 0, v[128:129]
	s_add_i32 m0, s43, 0x2000
	s_nop 0
	global_load_lds_dwordx4 v[226:227], off
	s_waitcnt vmcnt(4)
	s_waitcnt lgkmcnt(0)
	s_barrier
	s_setprio 1
	s_waitcnt lgkmcnt(0)
	v_mfma_f32_16x16x32_bf16 v[60:63], v[146:149], v[184:187], v[60:63]
	v_mfma_f32_16x16x32_bf16 v[56:59], v[160:163], v[184:187], v[56:59]
	v_mfma_f32_16x16x32_bf16 v[44:47], v[146:149], v[192:195], v[44:47]
	v_mfma_f32_16x16x32_bf16 v[40:43], v[160:163], v[192:195], v[40:43]
	v_mfma_f32_16x16x32_bf16 v[28:31], v[146:149], v[208:211], v[28:31]
	v_mfma_f32_16x16x32_bf16 v[24:27], v[160:163], v[208:211], v[24:27]
	v_mfma_f32_16x16x32_bf16 v[12:15], v[146:149], v[216:219], v[12:15]
	v_mfma_f32_16x16x32_bf16 v[8:11], v[160:163], v[216:219], v[8:11]
	v_mfma_f32_16x16x32_bf16 v[60:63], v[156:159], v[188:191], v[60:63]
	v_mfma_f32_16x16x32_bf16 v[56:59], v[164:167], v[188:191], v[56:59]
	v_mfma_f32_16x16x32_bf16 v[44:47], v[156:159], v[196:199], v[44:47]
	v_mfma_f32_16x16x32_bf16 v[40:43], v[164:167], v[196:199], v[40:43]
	v_mfma_f32_16x16x32_bf16 v[28:31], v[156:159], v[212:215], v[28:31]
	v_mfma_f32_16x16x32_bf16 v[24:27], v[164:167], v[212:215], v[24:27]
	v_mfma_f32_16x16x32_bf16 v[12:15], v[156:159], v[220:223], v[12:15]
	v_mfma_f32_16x16x32_bf16 v[8:11], v[164:167], v[220:223], v[8:11]
	s_setprio 0
	s_setprio 1
	v_mfma_f32_16x16x32_bf16 v[52:55], v[168:171], v[184:187], v[52:55]
	v_mfma_f32_16x16x32_bf16 v[48:51], v[176:179], v[184:187], v[48:51]
	v_mfma_f32_16x16x32_bf16 v[36:39], v[168:171], v[192:195], v[36:39]
	v_mfma_f32_16x16x32_bf16 v[32:35], v[176:179], v[192:195], v[32:35]
	v_mfma_f32_16x16x32_bf16 v[20:23], v[168:171], v[208:211], v[20:23]
	v_mfma_f32_16x16x32_bf16 v[16:19], v[176:179], v[208:211], v[16:19]
	v_mfma_f32_16x16x32_bf16 v[4:7], v[168:171], v[216:219], v[4:7]
	v_mfma_f32_16x16x32_bf16 v[0:3], v[176:179], v[216:219], v[0:3]
	v_mfma_f32_16x16x32_bf16 v[52:55], v[172:175], v[188:191], v[52:55]
	v_mfma_f32_16x16x32_bf16 v[48:51], v[180:183], v[188:191], v[48:51]
	v_mfma_f32_16x16x32_bf16 v[36:39], v[172:175], v[196:199], v[36:39]
	v_mfma_f32_16x16x32_bf16 v[32:35], v[180:183], v[196:199], v[32:35]
	v_mfma_f32_16x16x32_bf16 v[20:23], v[172:175], v[212:215], v[20:23]
	v_mfma_f32_16x16x32_bf16 v[16:19], v[180:183], v[212:215], v[16:19]
	v_mfma_f32_16x16x32_bf16 v[4:7], v[172:175], v[220:223], v[4:7]
	v_mfma_f32_16x16x32_bf16 v[0:3], v[180:183], v[220:223], v[0:3]
	s_setprio 0
	s_barrier
; #define PG8_STAGE(bufoff, gbase, voff) do { _Pragma("unroll") for (int _i = 0; _i < 2; ++_i) \
;         __builtin_amdgcn_global_load_lds((const unsigned*)((const char*)(gbase) + (voff)[_i]), (PG8_LAS unsigned*)(lds + (bufoff) + ldsw + _i * 8192), 16, 0, 0); } while (0)
; #define PG8_LDA(dst, b, h) do { _Pragma("unroll") for (int m = 0; m < 4; ++m) _Pragma("unroll") for (int k = 0; k < 2; ++k) dst[m][k] = *(const PG8_LAS bf16x8*)(lds + PG8_SA(b, h) + aoff + m * 2048 + k * 1024); } while (0)
; #define PG8_LDB(dst, b, h) do { _Pragma("unroll") for (int n = 0; n < 2; ++n) _Pragma("unroll") for (int k = 0; k < 2; ++k) dst[n][k] = *(const PG8_LAS bf16x8*)(lds + PG8_SB(b, h) + boff + n * 2048 + k * 1024); } while (0)
; #define PG8_MMA(ai, bj, At, Bt) do { __builtin_amdgcn_s_setprio(1); _Pragma("unroll") for (int m = 0; m < 4; ++m) _Pragma("unroll") for (int n = 0; n < 2; ++n) _Pragma("unroll") for (int k = 0; k < 2; ++k) \
;         acc[ai][bj][m][n] = __builtin_amdgcn_mfma_f32_16x16x32_bf16(Bt[n][k], At[m][k], acc[ai][bj][m][n], 0, 0, 0); __builtin_amdgcn_s_setprio(0); } while (0)
; #define PG8_WAIT_V(n) asm volatile("s_waitcnt vmcnt(" #n ")" ::: "memory")
; #define PG8_WAIT_L(n) asm volatile("s_waitcnt lgkmcnt(" #n ")" ::: "memory")
; #define PG8_BAR __builtin_amdgcn_s_barrier()
; #define PG8_SCHED __builtin_amdgcn_sched_barrier(0)
; template <class Epi, class Sched, bool ALIGN_EPI = false, bool SP2 = false>
; __device__ __forceinline__ void gemm_phase(PG8_LAS unsigned char* lds, const Gemm g, const Sched& S, const Epi& E) {
;     ...
;             PG8_LDB(B0, 1, 0); PG8_LDB(B1, 1, 1); PG8_SCHED; PG8_LDA(At, 1, 0); PG8_STAGE(PG8_SA(0, 1), a2 + hstep, voffA);
;             PG8_WAIT_V(8); PG8_WAIT_L(0); PG8_BAR; PG8_MMA(0, 0, At, B0); PG8_MMA(0, 1, At, B1); PG8_BAR; PG8_SCHED;
	s_add_i32 s43, 0, 0x18000
	v_add_u32_e32 v155, s43, v151
	s_add_i32 s61, 0, 0x1c000
	ds_read_b128 v[146:149], v155
	ds_read_b128 v[156:159], v155 offset:1024
	ds_read_b128 v[160:163], v155 offset:2048
	ds_read_b128 v[164:167], v155 offset:3072
	v_add_u32_e32 v155, s61, v151
	ds_read_b128 v[168:171], v155
	ds_read_b128 v[172:175], v155 offset:1024
	ds_read_b128 v[176:179], v155 offset:2048
	ds_read_b128 v[180:183], v155 offset:3072
	v_lshl_add_u64 v[226:227], s[36:37], 0, v[132:133]
	s_mov_b32 m0, s63
	s_nop 0
	global_load_lds_dwordx4 v[226:227], off
	v_lshl_add_u64 v[228:229], s[36:37], 0, v[130:131]
	s_mov_b32 m0, s64
	s_nop 0
	global_load_lds_dwordx4 v[228:229], off
	s_add_u32 s36, s36, 0x80000
	s_addc_u32 s37, s37, 0
	s_mov_b32 m0, s65
	v_lshl_add_u64 v[230:231], s[36:37], 0, v[132:133]
	ds_read_b128 v[184:187], v154 offset:32768
	ds_read_b128 v[188:191], v154 offset:33792
	ds_read_b128 v[192:195], v154 offset:34816
	ds_read_b128 v[196:199], v154 offset:35840
	ds_read_b128 v[208:211], v154 offset:36864
	ds_read_b128 v[212:215], v154 offset:37888
	ds_read_b128 v[216:219], v154 offset:38912
	ds_read_b128 v[220:223], v154 offset:39936
	global_load_lds_dwordx4 v[230:231], off
	v_lshl_add_u64 v[230:231], s[36:37], 0, v[130:131]
	s_mov_b32 m0, s67
	s_nop 0
	global_load_lds_dwordx4 v[230:231], off
	s_waitcnt vmcnt(8)
	s_waitcnt lgkmcnt(0)
	s_barrier
	s_setprio 1
	s_waitcnt lgkmcnt(0)
	v_mfma_f32_16x16x32_bf16 v[124:127], v[146:149], v[184:187], v[124:127]
	v_mfma_f32_16x16x32_bf16 v[120:123], v[160:163], v[184:187], v[120:123]
	v_mfma_f32_16x16x32_bf16 v[108:111], v[146:149], v[192:195], v[108:111]
	v_mfma_f32_16x16x32_bf16 v[104:107], v[160:163], v[192:195], v[104:107]
	v_mfma_f32_16x16x32_bf16 v[92:95], v[146:149], v[208:211], v[92:95]
	v_mfma_f32_16x16x32_bf16 v[88:91], v[160:163], v[208:211], v[88:91]
	v_mfma_f32_16x16x32_bf16 v[76:79], v[146:149], v[216:219], v[76:79]
	v_mfma_f32_16x16x32_bf16 v[72:75], v[160:163], v[216:219], v[72:75]
	v_mfma_f32_16x16x32_bf16 v[124:127], v[156:159], v[188:191], v[124:127]
	v_mfma_f32_16x16x32_bf16 v[120:123], v[164:167], v[188:191], v[120:123]
	v_mfma_f32_16x16x32_bf16 v[108:111], v[156:159], v[196:199], v[108:111]
	v_mfma_f32_16x16x32_bf16 v[104:107], v[164:167], v[196:199], v[104:107]
	v_mfma_f32_16x16x32_bf16 v[92:95], v[156:159], v[212:215], v[92:95]
	v_mfma_f32_16x16x32_bf16 v[88:91], v[164:167], v[212:215], v[88:91]
	v_mfma_f32_16x16x32_bf16 v[76:79], v[156:159], v[220:223], v[76:79]
	v_mfma_f32_16x16x32_bf16 v[72:75], v[164:167], v[220:223], v[72:75]
	s_setprio 0
	s_setprio 1
	v_mfma_f32_16x16x32_bf16 v[116:119], v[168:171], v[184:187], v[116:119]
	v_mfma_f32_16x16x32_bf16 v[112:115], v[176:179], v[184:187], v[112:115]
	v_mfma_f32_16x16x32_bf16 v[100:103], v[168:171], v[192:195], v[100:103]
	v_mfma_f32_16x16x32_bf16 v[96:99], v[176:179], v[192:195], v[96:99]
	v_mfma_f32_16x16x32_bf16 v[84:87], v[168:171], v[208:211], v[84:87]
	v_mfma_f32_16x16x32_bf16 v[80:83], v[176:179], v[208:211], v[80:83]
	v_mfma_f32_16x16x32_bf16 v[68:71], v[168:171], v[216:219], v[68:71]
	v_mfma_f32_16x16x32_bf16 v[64:67], v[176:179], v[216:219], v[64:67]
	v_mfma_f32_16x16x32_bf16 v[116:119], v[172:175], v[188:191], v[116:119]
	v_mfma_f32_16x16x32_bf16 v[112:115], v[180:183], v[188:191], v[112:115]
	v_mfma_f32_16x16x32_bf16 v[100:103], v[172:175], v[196:199], v[100:103]
	v_mfma_f32_16x16x32_bf16 v[96:99], v[180:183], v[196:199], v[96:99]
	v_mfma_f32_16x16x32_bf16 v[84:87], v[172:175], v[212:215], v[84:87]
	v_mfma_f32_16x16x32_bf16 v[80:83], v[180:183], v[212:215], v[80:83]
	v_mfma_f32_16x16x32_bf16 v[68:71], v[172:175], v[220:223], v[68:71]
	v_mfma_f32_16x16x32_bf16 v[64:67], v[180:183], v[220:223], v[64:67]
	s_setprio 0
	s_barrier
; #define PG8_STAGE(bufoff, gbase, voff) do { _Pragma("unroll") for (int _i = 0; _i < 2; ++_i) \
;         __builtin_amdgcn_global_load_lds((const unsigned*)((const char*)(gbase) + (voff)[_i]), (PG8_LAS unsigned*)(lds + (bufoff) + ldsw + _i * 8192), 16, 0, 0); } while (0)
; #define PG8_LDA(dst, b, h) do { _Pragma("unroll") for (int m = 0; m < 4; ++m) _Pragma("unroll") for (int k = 0; k < 2; ++k) dst[m][k] = *(const PG8_LAS bf16x8*)(lds + PG8_SA(b, h) + aoff + m * 2048 + k * 1024); } while (0)
; #define PG8_MMA(ai, bj, At, Bt) do { __builtin_amdgcn_s_setprio(1); _Pragma("unroll") for (int m = 0; m < 4; ++m) _Pragma("unroll") for (int n = 0; n < 2; ++n) _Pragma("unroll") for (int k = 0; k < 2; ++k) \
;         acc[ai][bj][m][n] = __builtin_amdgcn_mfma_f32_16x16x32_bf16(Bt[n][k], At[m][k], acc[ai][bj][m][n], 0, 0, 0); __builtin_amdgcn_s_setprio(0); } while (0)
; #define PG8_WAIT_V(n) asm volatile("s_waitcnt vmcnt(" #n ")" ::: "memory")
; #define PG8_WAIT_L(n) asm volatile("s_waitcnt lgkmcnt(" #n ")" ::: "memory")
; #define PG8_BAR __builtin_amdgcn_s_barrier()
; #define PG8_SCHED __builtin_amdgcn_sched_barrier(0)
; template <class Epi, class Sched, bool ALIGN_EPI = false, bool SP2 = false>
; __device__ __forceinline__ void gemm_phase(PG8_LAS unsigned char* lds, const Gemm g, const Sched& S, const Epi& E) {
;     ...
;         for (int t = 0; t < nt; t += 2) {
;     ...
;             PG8_LDA(At, 1, 1); PG8_STAGE(PG8_SB(1, 0), b3, voffB); PG8_STAGE(PG8_SB(1, 1), b3 + hstep, voffB); PG8_STAGE(PG8_SA(1, 0), a3, voffA);
;             PG8_WAIT_V(8); PG8_WAIT_L(0); PG8_BAR; PG8_MMA(1, 0, At, B0); PG8_MMA(1, 1, At, B1); PG8_BAR; PG8_SCHED;
	s_add_i32 s36, s43, s62
	v_lshl_add_u64 v[138:139], v[138:139], 0, s[84:85]
	s_mov_b32 m0, s36
	ds_read_b128 v[184:187], v154 offset:49152
	ds_read_b128 v[188:191], v154 offset:50176
	ds_read_b128 v[192:195], v154 offset:51200
	ds_read_b128 v[196:199], v154 offset:52224
	ds_read_b128 v[208:211], v154 offset:53248
	ds_read_b128 v[212:215], v154 offset:54272
	ds_read_b128 v[216:219], v154 offset:55296
	ds_read_b128 v[220:223], v154 offset:56320
	global_load_lds_dwordx4 v[138:139], off
	s_add_i32 m0, s36, 0x2000
	s_add_u32 s26, s26, 0x80080
	v_lshl_add_u64 v[138:139], v[224:225], 0, s[84:85]
	s_addc_u32 s27, s27, 0
	s_add_i32 s36, s61, s62
	global_load_lds_dwordx4 v[138:139], off
	v_lshl_add_u64 v[138:139], s[26:27], 0, v[140:141]
	s_mov_b32 m0, s36
	s_nop 0
	global_load_lds_dwordx4 v[138:139], off
	v_lshl_add_u64 v[138:139], s[26:27], 0, v[128:129]
	s_add_i32 m0, s36, 0x2000
	s_nop 0
	global_load_lds_dwordx4 v[138:139], off
	s_waitcnt vmcnt(4)
	s_waitcnt lgkmcnt(0)
	s_barrier
	s_setprio 1
	s_waitcnt lgkmcnt(0)
	v_mfma_f32_16x16x32_bf16 v[60:63], v[146:149], v[184:187], v[60:63]
	v_mfma_f32_16x16x32_bf16 v[56:59], v[160:163], v[184:187], v[56:59]
	v_mfma_f32_16x16x32_bf16 v[44:47], v[146:149], v[192:195], v[44:47]
	v_mfma_f32_16x16x32_bf16 v[40:43], v[160:163], v[192:195], v[40:43]
	v_mfma_f32_16x16x32_bf16 v[28:31], v[146:149], v[208:211], v[28:31]
	v_mfma_f32_16x16x32_bf16 v[24:27], v[160:163], v[208:211], v[24:27]
	v_mfma_f32_16x16x32_bf16 v[12:15], v[146:149], v[216:219], v[12:15]
	v_mfma_f32_16x16x32_bf16 v[8:11], v[160:163], v[216:219], v[8:11]
	v_mfma_f32_16x16x32_bf16 v[60:63], v[156:159], v[188:191], v[60:63]
	v_mfma_f32_16x16x32_bf16 v[56:59], v[164:167], v[188:191], v[56:59]
	v_mfma_f32_16x16x32_bf16 v[44:47], v[156:159], v[196:199], v[44:47]
	v_mfma_f32_16x16x32_bf16 v[40:43], v[164:167], v[196:199], v[40:43]
	v_mfma_f32_16x16x32_bf16 v[28:31], v[156:159], v[212:215], v[28:31]
	v_mfma_f32_16x16x32_bf16 v[24:27], v[164:167], v[212:215], v[24:27]
	v_mfma_f32_16x16x32_bf16 v[12:15], v[156:159], v[220:223], v[12:15]
	v_mfma_f32_16x16x32_bf16 v[8:11], v[164:167], v[220:223], v[8:11]
	s_setprio 0
	s_setprio 1
	v_mfma_f32_16x16x32_bf16 v[52:55], v[168:171], v[184:187], v[52:55]
	v_mfma_f32_16x16x32_bf16 v[48:51], v[176:179], v[184:187], v[48:51]
	v_mfma_f32_16x16x32_bf16 v[36:39], v[168:171], v[192:195], v[36:39]
	v_mfma_f32_16x16x32_bf16 v[32:35], v[176:179], v[192:195], v[32:35]
	v_mfma_f32_16x16x32_bf16 v[20:23], v[168:171], v[208:211], v[20:23]
	v_mfma_f32_16x16x32_bf16 v[16:19], v[176:179], v[208:211], v[16:19]
	v_mfma_f32_16x16x32_bf16 v[4:7], v[168:171], v[216:219], v[4:7]
	v_mfma_f32_16x16x32_bf16 v[0:3], v[176:179], v[216:219], v[0:3]
	v_mfma_f32_16x16x32_bf16 v[52:55], v[172:175], v[188:191], v[52:55]
	v_mfma_f32_16x16x32_bf16 v[48:51], v[180:183], v[188:191], v[48:51]
	v_mfma_f32_16x16x32_bf16 v[36:39], v[172:175], v[196:199], v[36:39]
	v_mfma_f32_16x16x32_bf16 v[32:35], v[180:183], v[196:199], v[32:35]
	v_mfma_f32_16x16x32_bf16 v[20:23], v[172:175], v[212:215], v[20:23]
	v_mfma_f32_16x16x32_bf16 v[16:19], v[180:183], v[212:215], v[16:19]
	v_mfma_f32_16x16x32_bf16 v[4:7], v[172:175], v[220:223], v[4:7]
	v_mfma_f32_16x16x32_bf16 v[0:3], v[180:183], v[220:223], v[0:3]
	s_setprio 0
	s_barrier
	s_add_i32 s76, s76, 2
	s_add_u32 s22, s22, 0x100
	s_addc_u32 s23, s23, 0
	s_add_u32 s56, s56, 0x100
	s_addc_u32 s73, s73, 0
	s_cmp_gt_u32 s76, 29
	s_cbranch_scc0 .LBB0_1010
	s_and_b64 vcc, exec, s[10:11]
	s_cbranch_vccz .LBB0_1013
	s_barrier
